# once-read gate loads of the gated-merge hook and epilogue marked nt so the 64 MB gate stream does not displace the GEMM tiles in L2
# baseline (speedup 1.0000x reference)
.LBB0_263:
	v_mov_b32_e32 v130, v1
	v_mov_b32_e32 v131, v154
	s_and_b32 s22, s20, 0xc00
	v_add_u32_e32 v157, s64, v130
	v_lshl_add_u32 v166, v131, 3, s65
	v_add_u32_e32 v131, s93, v157
	v_mov_b64_e32 v[132:133], s[10:11]
	s_add_i32 s40, s22, 0xfffffc00
	v_add_u32_e32 v130, s92, v166
	v_mad_i64_i32 v[134:135], s[22:23], v131, s24, v[132:133]
	s_lshl_b64 s[22:23], s[40:41], 1
	v_ashrrev_i32_e32 v131, 31, v130
	v_lshl_add_u64 v[136:137], v[134:135], 0, s[22:23]
	v_lshlrev_b64 v[134:135], 1, v[130:131]
	v_lshl_add_u64 v[130:131], v[136:137], 0, v[134:135]
	v_mov_b32_e32 v206, v130
	v_mov_b32_e32 v207, v131
	v_add_u32_e32 v130, s94, v166
	v_ashrrev_i32_e32 v131, 31, v130
	v_lshlrev_b64 v[130:131], 1, v[130:131]
	v_lshl_add_u64 v[136:137], v[136:137], 0, v[130:131]
	v_mov_b32_e32 v208, v136
	v_mov_b32_e32 v209, v137
	v_add_u32_e32 v136, s95, v157
	v_mad_i64_i32 v[136:137], s[26:27], v136, s24, v[132:133]
	v_lshl_add_u64 v[136:137], v[136:137], 0, s[22:23]
	v_lshl_add_u64 v[162:163], v[136:137], 0, v[134:135]
	v_mov_b32_e32 v210, v162
	v_mov_b32_e32 v211, v163
	v_lshl_add_u64 v[136:137], v[136:137], 0, v[130:131]
	v_mov_b32_e32 v212, v136
	v_mov_b32_e32 v213, v137
	v_add_u32_e32 v136, s96, v157
	v_mad_i64_i32 v[136:137], s[26:27], v136, s24, v[132:133]
	v_lshl_add_u64 v[136:137], v[136:137], 0, s[22:23]
	v_lshl_add_u64 v[162:163], v[136:137], 0, v[134:135]
	v_mov_b32_e32 v214, v162
	v_mov_b32_e32 v215, v163
	v_lshl_add_u64 v[136:137], v[136:137], 0, v[130:131]
	v_mov_b32_e32 v216, v136
	v_mov_b32_e32 v217, v137
	v_add_u32_e32 v136, s97, v157
	v_mad_i64_i32 v[136:137], s[26:27], v136, s24, v[132:133]
	v_lshl_add_u64 v[136:137], v[136:137], 0, s[22:23]
	v_lshl_add_u64 v[162:163], v[136:137], 0, v[134:135]
	v_mov_b32_e32 v218, v162
	v_mov_b32_e32 v219, v163
	v_lshl_add_u64 v[136:137], v[136:137], 0, v[130:131]
	v_mov_b32_e32 v220, v136
	v_mov_b32_e32 v221, v137
	v_add_u32_e32 v136, s37, v157
	v_mad_i64_i32 v[136:137], s[26:27], v136, s24, v[132:133]
	v_lshl_add_u64 v[136:137], v[136:137], 0, s[22:23]
	v_lshl_add_u64 v[162:163], v[136:137], 0, v[134:135]
	v_mov_b32_e32 v222, v162
	v_mov_b32_e32 v223, v163
	v_lshl_add_u64 v[136:137], v[136:137], 0, v[130:131]
	v_mov_b32_e32 v226, v136
	v_mov_b32_e32 v227, v137
	v_add_u32_e32 v136, s89, v157
	v_mad_i64_i32 v[136:137], s[26:27], v136, s24, v[132:133]
	v_lshl_add_u64 v[136:137], v[136:137], 0, s[22:23]
	v_lshl_add_u64 v[162:163], v[136:137], 0, v[134:135]
	v_mov_b32_e32 v232, v162
	v_mov_b32_e32 v233, v163
	v_lshl_add_u64 v[136:137], v[136:137], 0, v[130:131]
	v_mov_b32_e32 v240, v136
	v_mov_b32_e32 v241, v137
	v_add_u32_e32 v136, s1, v157
	v_mad_i64_i32 v[136:137], s[26:27], v136, s24, v[132:133]
	v_lshl_add_u64 v[136:137], v[136:137], 0, s[22:23]
	v_lshl_add_u64 v[162:163], v[136:137], 0, v[134:135]
	v_mov_b32_e32 v242, v162
	v_mov_b32_e32 v243, v163
	v_lshl_add_u64 v[136:137], v[136:137], 0, v[130:131]
	v_mov_b32_e32 v244, v136
	v_mov_b32_e32 v245, v137
	v_add_u32_e32 v136, s0, v157
	v_mad_i64_i32 v[132:133], s[26:27], v136, s24, v[132:133]
	v_lshl_add_u64 v[132:133], v[132:133], 0, s[22:23]
	v_lshl_add_u64 v[158:159], v[132:133], 0, v[134:135]
	v_mov_b32_e32 v246, v158
	v_mov_b32_e32 v247, v159
	v_lshl_add_u64 v[134:135], v[132:133], 0, v[130:131]
	v_mov_b32_e32 v248, v134
	v_mov_b32_e32 v249, v135
	global_load_dwordx4 v[174:177], v[206:207], off nt
	global_load_dwordx4 v[178:181], v[206:207], off offset:2048 nt
	global_load_dwordx4 v[182:185], v[208:209], off nt
	global_load_dwordx4 v[186:189], v[208:209], off offset:2048 nt
	global_load_dwordx4 v[190:193], v[210:211], off nt
	global_load_dwordx4 v[194:197], v[210:211], off offset:2048 nt
	s_waitcnt vmcnt(4)
	v_lshlrev_b32_e32 v130, 16, v178
	v_and_b32_e32 v131, 0xffff0000, v178
	v_rcp_f32_e32 v130, v130
	v_rcp_f32_e32 v131, v131
	v_lshlrev_b32_e32 v167, 16, v179
	v_and_b32_e32 v168, 0xffff0000, v179
	v_lshlrev_b32_e32 v162, 16, v180
	v_and_b32_e32 v163, 0xffff0000, v180
	v_rcp_f32_e32 v162, v162
	v_rcp_f32_e32 v163, v163
	v_lshlrev_b32_e32 v169, 16, v181
	v_and_b32_e32 v170, 0xffff0000, v181
	v_lshlrev_b32_e32 v164, 16, v174
	v_and_b32_e32 v165, 0xffff0000, v174
	v_pk_mul_f32 v[130:131], v[130:131], v[164:165]
	v_rcp_f32_e32 v158, v169
	v_pk_mul_f32 v[126:127], v[126:127], v[130:131]
	v_lshlrev_b32_e32 v130, 16, v176
	v_and_b32_e32 v131, 0xffff0000, v176
	v_pk_mul_f32 v[130:131], v[162:163], v[130:131]
	v_lshlrev_b32_e32 v162, 16, v175
	v_pk_mul_f32 v[122:123], v[122:123], v[130:131]
	v_rcp_f32_e32 v130, v167
	v_rcp_f32_e32 v131, v168
	v_and_b32_e32 v163, 0xffff0000, v175
	v_rcp_f32_e32 v159, v170
	v_pk_mul_f32 v[130:131], v[130:131], v[162:163]
	s_nop 0
	v_pk_mul_f32 v[128:129], v[128:129], v[130:131]
	v_lshlrev_b32_e32 v130, 16, v177
	v_and_b32_e32 v131, 0xffff0000, v177
	v_pk_mul_f32 v[130:131], v[158:159], v[130:131]
	s_nop 0
	v_pk_mul_f32 v[124:125], v[124:125], v[130:131]
	global_load_dwordx4 v[198:201], v[212:213], off nt
	global_load_dwordx4 v[202:205], v[212:213], off offset:2048 nt
	s_waitcnt vmcnt(4)
	v_lshlrev_b32_e32 v136, 16, v186
	v_and_b32_e32 v137, 0xffff0000, v186
	v_rcp_f32_e32 v136, v136
	v_rcp_f32_e32 v137, v137
	v_lshlrev_b32_e32 v166, 16, v187
	v_and_b32_e32 v167, 0xffff0000, v187
	v_lshlrev_b32_e32 v162, 16, v188
	v_and_b32_e32 v163, 0xffff0000, v188
	v_rcp_f32_e32 v162, v162
	v_rcp_f32_e32 v163, v163
	v_lshlrev_b32_e32 v168, 16, v189
	v_and_b32_e32 v169, 0xffff0000, v189
	v_lshlrev_b32_e32 v164, 16, v182
	v_and_b32_e32 v165, 0xffff0000, v182
	v_pk_mul_f32 v[136:137], v[136:137], v[164:165]
	v_rcp_f32_e32 v158, v168
	v_pk_mul_f32 v[118:119], v[118:119], v[136:137]
	v_lshlrev_b32_e32 v136, 16, v184
	v_and_b32_e32 v137, 0xffff0000, v184
	v_pk_mul_f32 v[136:137], v[162:163], v[136:137]
	v_lshlrev_b32_e32 v162, 16, v183
	v_pk_mul_f32 v[114:115], v[114:115], v[136:137]
	v_rcp_f32_e32 v136, v166
	v_rcp_f32_e32 v137, v167
	v_and_b32_e32 v163, 0xffff0000, v183
	v_rcp_f32_e32 v159, v169
	v_pk_mul_f32 v[136:137], v[136:137], v[162:163]
	s_nop 0
	v_pk_mul_f32 v[120:121], v[120:121], v[136:137]
	v_lshlrev_b32_e32 v136, 16, v185
	v_and_b32_e32 v137, 0xffff0000, v185
	v_pk_mul_f32 v[136:137], v[158:159], v[136:137]
	s_nop 0
	v_pk_mul_f32 v[116:117], v[116:117], v[136:137]
	global_load_dwordx4 v[174:177], v[214:215], off nt
	global_load_dwordx4 v[178:181], v[214:215], off offset:2048 nt
	s_waitcnt vmcnt(4)
	s_nop 0
	v_lshlrev_b32_e32 v166, 16, v194
	v_and_b32_e32 v167, 0xffff0000, v194
	v_lshlrev_b32_e32 v168, 16, v195
	v_and_b32_e32 v169, 0xffff0000, v195
	v_lshlrev_b32_e32 v163, 16, v196
	v_and_b32_e32 v170, 0xffff0000, v196
	v_rcp_f32_e32 v162, v166
	v_rcp_f32_e32 v164, v163
	v_rcp_f32_e32 v163, v167
	v_lshlrev_b32_e32 v171, 16, v197
	v_and_b32_e32 v172, 0xffff0000, v197
	v_rcp_f32_e32 v165, v170
	v_lshlrev_b32_e32 v166, 16, v190
	v_and_b32_e32 v167, 0xffff0000, v190
	v_pk_mul_f32 v[162:163], v[162:163], v[166:167]
	v_rcp_f32_e32 v158, v171
	v_pk_mul_f32 v[110:111], v[110:111], v[162:163]
	v_lshlrev_b32_e32 v162, 16, v192
	v_and_b32_e32 v163, 0xffff0000, v192
	v_pk_mul_f32 v[162:163], v[164:165], v[162:163]
	v_lshlrev_b32_e32 v164, 16, v191
	v_pk_mul_f32 v[106:107], v[106:107], v[162:163]
	v_rcp_f32_e32 v162, v168
	v_rcp_f32_e32 v163, v169
	v_and_b32_e32 v165, 0xffff0000, v191
	v_rcp_f32_e32 v159, v172
	v_lshlrev_b32_e32 v160, 16, v193
	v_and_b32_e32 v161, 0xffff0000, v193
	v_pk_mul_f32 v[162:163], v[162:163], v[164:165]
	v_pk_mul_f32 v[158:159], v[158:159], v[160:161]
	v_pk_mul_f32 v[112:113], v[112:113], v[162:163]
	v_pk_mul_f32 v[108:109], v[108:109], v[158:159]
	global_load_dwordx4 v[182:185], v[216:217], off nt
	global_load_dwordx4 v[186:189], v[216:217], off offset:2048 nt
	s_waitcnt vmcnt(4)
	v_lshlrev_b32_e32 v136, 16, v202
	v_and_b32_e32 v137, 0xffff0000, v202
	v_rcp_f32_e32 v136, v136
	v_rcp_f32_e32 v137, v137
	v_lshlrev_b32_e32 v166, 16, v203
	v_and_b32_e32 v167, 0xffff0000, v203
	v_lshlrev_b32_e32 v162, 16, v204
	v_and_b32_e32 v163, 0xffff0000, v204
	v_rcp_f32_e32 v162, v162
	v_rcp_f32_e32 v163, v163
	v_lshlrev_b32_e32 v168, 16, v205
	v_and_b32_e32 v169, 0xffff0000, v205
	v_lshlrev_b32_e32 v164, 16, v198
	v_and_b32_e32 v165, 0xffff0000, v198
	v_pk_mul_f32 v[136:137], v[136:137], v[164:165]
	v_rcp_f32_e32 v158, v168
	v_pk_mul_f32 v[102:103], v[102:103], v[136:137]
	v_lshlrev_b32_e32 v136, 16, v200
	v_and_b32_e32 v137, 0xffff0000, v200
	v_pk_mul_f32 v[136:137], v[162:163], v[136:137]
	v_lshlrev_b32_e32 v162, 16, v199
	v_pk_mul_f32 v[98:99], v[98:99], v[136:137]
	v_rcp_f32_e32 v136, v166
	v_rcp_f32_e32 v137, v167
	v_and_b32_e32 v163, 0xffff0000, v199
	v_rcp_f32_e32 v159, v169
	v_pk_mul_f32 v[136:137], v[136:137], v[162:163]
	s_nop 0
	v_pk_mul_f32 v[104:105], v[104:105], v[136:137]
	v_lshlrev_b32_e32 v136, 16, v201
	v_and_b32_e32 v137, 0xffff0000, v201
	v_pk_mul_f32 v[136:137], v[158:159], v[136:137]
	s_nop 0
	v_pk_mul_f32 v[100:101], v[100:101], v[136:137]
	global_load_dwordx4 v[190:193], v[218:219], off nt
	global_load_dwordx4 v[194:197], v[218:219], off offset:2048 nt
	s_waitcnt vmcnt(4)
	s_nop 0
	v_lshlrev_b32_e32 v166, 16, v178
	v_and_b32_e32 v167, 0xffff0000, v178
	v_lshlrev_b32_e32 v168, 16, v179
	v_and_b32_e32 v169, 0xffff0000, v179
	v_lshlrev_b32_e32 v163, 16, v180
	v_and_b32_e32 v170, 0xffff0000, v180
	v_rcp_f32_e32 v162, v166
	v_rcp_f32_e32 v164, v163
	v_rcp_f32_e32 v163, v167
	v_lshlrev_b32_e32 v171, 16, v181
	v_and_b32_e32 v172, 0xffff0000, v181
	v_rcp_f32_e32 v165, v170
	v_lshlrev_b32_e32 v166, 16, v174
	v_and_b32_e32 v167, 0xffff0000, v174
	v_pk_mul_f32 v[162:163], v[162:163], v[166:167]
	v_rcp_f32_e32 v158, v171
	v_pk_mul_f32 v[94:95], v[94:95], v[162:163]
	v_lshlrev_b32_e32 v162, 16, v176
	v_and_b32_e32 v163, 0xffff0000, v176
	v_pk_mul_f32 v[162:163], v[164:165], v[162:163]
	v_lshlrev_b32_e32 v164, 16, v175
	v_pk_mul_f32 v[90:91], v[90:91], v[162:163]
	v_rcp_f32_e32 v162, v168
	v_rcp_f32_e32 v163, v169
	v_and_b32_e32 v165, 0xffff0000, v175
	v_rcp_f32_e32 v159, v172
	v_lshlrev_b32_e32 v160, 16, v177
	v_and_b32_e32 v161, 0xffff0000, v177
	v_pk_mul_f32 v[162:163], v[162:163], v[164:165]
	v_pk_mul_f32 v[158:159], v[158:159], v[160:161]
	v_pk_mul_f32 v[96:97], v[96:97], v[162:163]
	v_pk_mul_f32 v[92:93], v[92:93], v[158:159]
	global_load_dwordx4 v[198:201], v[220:221], off nt
	global_load_dwordx4 v[202:205], v[220:221], off offset:2048 nt
	s_waitcnt vmcnt(4)
	v_lshlrev_b32_e32 v136, 16, v186
	v_and_b32_e32 v137, 0xffff0000, v186
	v_rcp_f32_e32 v136, v136
	v_rcp_f32_e32 v137, v137
	v_lshlrev_b32_e32 v166, 16, v187
	v_and_b32_e32 v167, 0xffff0000, v187
	v_lshlrev_b32_e32 v162, 16, v188
	v_and_b32_e32 v163, 0xffff0000, v188
	v_rcp_f32_e32 v162, v162
	v_rcp_f32_e32 v163, v163
	v_lshlrev_b32_e32 v168, 16, v189
	v_and_b32_e32 v169, 0xffff0000, v189
	v_lshlrev_b32_e32 v164, 16, v182
	v_and_b32_e32 v165, 0xffff0000, v182
	v_pk_mul_f32 v[136:137], v[136:137], v[164:165]
	v_rcp_f32_e32 v158, v168
	v_pk_mul_f32 v[86:87], v[86:87], v[136:137]
	v_lshlrev_b32_e32 v136, 16, v184
	v_and_b32_e32 v137, 0xffff0000, v184
	v_pk_mul_f32 v[136:137], v[162:163], v[136:137]
	v_lshlrev_b32_e32 v162, 16, v183
	v_pk_mul_f32 v[82:83], v[82:83], v[136:137]
	v_rcp_f32_e32 v136, v166
	v_rcp_f32_e32 v137, v167
	v_and_b32_e32 v163, 0xffff0000, v183
	v_rcp_f32_e32 v159, v169
	v_pk_mul_f32 v[136:137], v[136:137], v[162:163]
	s_nop 0
	v_pk_mul_f32 v[88:89], v[88:89], v[136:137]
	v_lshlrev_b32_e32 v136, 16, v185
	v_and_b32_e32 v137, 0xffff0000, v185
	v_pk_mul_f32 v[136:137], v[158:159], v[136:137]
	s_nop 0
	v_pk_mul_f32 v[84:85], v[84:85], v[136:137]
	global_load_dwordx4 v[174:177], v[222:223], off nt
	global_load_dwordx4 v[178:181], v[222:223], off offset:2048 nt
	s_waitcnt vmcnt(4)
	s_nop 0
	v_lshlrev_b32_e32 v166, 16, v194
	v_and_b32_e32 v167, 0xffff0000, v194
	v_lshlrev_b32_e32 v168, 16, v195
	v_and_b32_e32 v169, 0xffff0000, v195
	v_lshlrev_b32_e32 v163, 16, v196
	v_and_b32_e32 v170, 0xffff0000, v196
	v_rcp_f32_e32 v162, v166
	v_rcp_f32_e32 v164, v163
	v_rcp_f32_e32 v163, v167
	v_lshlrev_b32_e32 v171, 16, v197
	v_and_b32_e32 v172, 0xffff0000, v197
	v_rcp_f32_e32 v165, v170
	v_lshlrev_b32_e32 v166, 16, v190
	v_and_b32_e32 v167, 0xffff0000, v190
	v_pk_mul_f32 v[162:163], v[162:163], v[166:167]
	v_rcp_f32_e32 v158, v171
	v_pk_mul_f32 v[78:79], v[78:79], v[162:163]
	v_lshlrev_b32_e32 v162, 16, v192
	v_and_b32_e32 v163, 0xffff0000, v192
	v_pk_mul_f32 v[162:163], v[164:165], v[162:163]
	v_lshlrev_b32_e32 v164, 16, v191
	v_pk_mul_f32 v[74:75], v[74:75], v[162:163]
	v_rcp_f32_e32 v162, v168
	v_rcp_f32_e32 v163, v169
	v_and_b32_e32 v165, 0xffff0000, v191
	v_rcp_f32_e32 v159, v172
	v_lshlrev_b32_e32 v160, 16, v193
	v_and_b32_e32 v161, 0xffff0000, v193
	v_pk_mul_f32 v[162:163], v[162:163], v[164:165]
	v_pk_mul_f32 v[158:159], v[158:159], v[160:161]
	v_pk_mul_f32 v[80:81], v[80:81], v[162:163]
	v_pk_mul_f32 v[76:77], v[76:77], v[158:159]
	global_load_dwordx4 v[182:185], v[226:227], off nt
	global_load_dwordx4 v[186:189], v[226:227], off offset:2048 nt
	s_waitcnt vmcnt(4)
	v_lshlrev_b32_e32 v136, 16, v202
	v_and_b32_e32 v137, 0xffff0000, v202
	v_rcp_f32_e32 v136, v136
	v_rcp_f32_e32 v137, v137
	v_lshlrev_b32_e32 v166, 16, v203
	v_and_b32_e32 v167, 0xffff0000, v203
	v_lshlrev_b32_e32 v162, 16, v204
	v_and_b32_e32 v163, 0xffff0000, v204
	v_rcp_f32_e32 v162, v162
	v_rcp_f32_e32 v163, v163
	v_lshlrev_b32_e32 v168, 16, v205
	v_and_b32_e32 v169, 0xffff0000, v205
	v_lshlrev_b32_e32 v164, 16, v198
	v_and_b32_e32 v165, 0xffff0000, v198
	v_pk_mul_f32 v[136:137], v[136:137], v[164:165]
	v_rcp_f32_e32 v158, v168
	v_pk_mul_f32 v[70:71], v[70:71], v[136:137]
	v_lshlrev_b32_e32 v136, 16, v200
	v_and_b32_e32 v137, 0xffff0000, v200
	v_pk_mul_f32 v[136:137], v[162:163], v[136:137]
	v_lshlrev_b32_e32 v162, 16, v199
	v_pk_mul_f32 v[66:67], v[66:67], v[136:137]
	v_rcp_f32_e32 v136, v166
	v_rcp_f32_e32 v137, v167
	v_and_b32_e32 v163, 0xffff0000, v199
	v_rcp_f32_e32 v159, v169
	v_pk_mul_f32 v[136:137], v[136:137], v[162:163]
	s_nop 0
	v_pk_mul_f32 v[72:73], v[72:73], v[136:137]
	v_lshlrev_b32_e32 v136, 16, v201
	v_and_b32_e32 v137, 0xffff0000, v201
	v_pk_mul_f32 v[136:137], v[158:159], v[136:137]
	s_nop 0
	v_pk_mul_f32 v[68:69], v[68:69], v[136:137]
	global_load_dwordx4 v[190:193], v[232:233], off nt
	global_load_dwordx4 v[194:197], v[232:233], off offset:2048 nt
	s_waitcnt vmcnt(4)
	s_nop 0
	v_lshlrev_b32_e32 v166, 16, v178
	v_and_b32_e32 v167, 0xffff0000, v178
	v_lshlrev_b32_e32 v168, 16, v179
	v_and_b32_e32 v169, 0xffff0000, v179
	v_lshlrev_b32_e32 v163, 16, v180
	v_and_b32_e32 v170, 0xffff0000, v180
	v_rcp_f32_e32 v162, v166
	v_rcp_f32_e32 v164, v163
	v_rcp_f32_e32 v163, v167
	v_lshlrev_b32_e32 v171, 16, v181
	v_and_b32_e32 v172, 0xffff0000, v181
	v_rcp_f32_e32 v165, v170
	v_lshlrev_b32_e32 v166, 16, v174
	v_and_b32_e32 v167, 0xffff0000, v174
	v_pk_mul_f32 v[162:163], v[162:163], v[166:167]
	v_rcp_f32_e32 v158, v171
	v_pk_mul_f32 v[62:63], v[62:63], v[162:163]
	v_lshlrev_b32_e32 v162, 16, v176
	v_and_b32_e32 v163, 0xffff0000, v176
	v_pk_mul_f32 v[162:163], v[164:165], v[162:163]
	v_lshlrev_b32_e32 v164, 16, v175
	v_pk_mul_f32 v[58:59], v[58:59], v[162:163]
	v_rcp_f32_e32 v162, v168
	v_rcp_f32_e32 v163, v169
	v_and_b32_e32 v165, 0xffff0000, v175
	v_rcp_f32_e32 v159, v172
	v_lshlrev_b32_e32 v160, 16, v177
	v_and_b32_e32 v161, 0xffff0000, v177
	v_pk_mul_f32 v[162:163], v[162:163], v[164:165]
	v_pk_mul_f32 v[158:159], v[158:159], v[160:161]
	v_pk_mul_f32 v[64:65], v[64:65], v[162:163]
	v_pk_mul_f32 v[60:61], v[60:61], v[158:159]
	global_load_dwordx4 v[198:201], v[240:241], off nt
	global_load_dwordx4 v[202:205], v[240:241], off offset:2048 nt
	s_waitcnt vmcnt(4)
	v_lshlrev_b32_e32 v136, 16, v186
	v_and_b32_e32 v137, 0xffff0000, v186
	v_rcp_f32_e32 v136, v136
	v_rcp_f32_e32 v137, v137
	v_lshlrev_b32_e32 v166, 16, v187
	v_and_b32_e32 v167, 0xffff0000, v187
	v_lshlrev_b32_e32 v162, 16, v188
	v_and_b32_e32 v163, 0xffff0000, v188
	v_rcp_f32_e32 v162, v162
	v_rcp_f32_e32 v163, v163
	v_lshlrev_b32_e32 v168, 16, v189
	v_and_b32_e32 v169, 0xffff0000, v189
	v_lshlrev_b32_e32 v164, 16, v182
	v_and_b32_e32 v165, 0xffff0000, v182
	v_pk_mul_f32 v[136:137], v[136:137], v[164:165]
	v_rcp_f32_e32 v158, v168
	v_pk_mul_f32 v[54:55], v[54:55], v[136:137]
	v_lshlrev_b32_e32 v136, 16, v184
	v_and_b32_e32 v137, 0xffff0000, v184
	v_pk_mul_f32 v[136:137], v[162:163], v[136:137]
	v_lshlrev_b32_e32 v162, 16, v183
	v_pk_mul_f32 v[50:51], v[50:51], v[136:137]
	v_rcp_f32_e32 v136, v166
	v_rcp_f32_e32 v137, v167
	v_and_b32_e32 v163, 0xffff0000, v183
	v_rcp_f32_e32 v159, v169
	v_pk_mul_f32 v[136:137], v[136:137], v[162:163]
	s_nop 0
	v_pk_mul_f32 v[56:57], v[56:57], v[136:137]
	v_lshlrev_b32_e32 v136, 16, v185
	v_and_b32_e32 v137, 0xffff0000, v185
	v_pk_mul_f32 v[136:137], v[158:159], v[136:137]
	s_nop 0
	v_pk_mul_f32 v[52:53], v[52:53], v[136:137]
	global_load_dwordx4 v[174:177], v[242:243], off nt
	global_load_dwordx4 v[178:181], v[242:243], off offset:2048 nt
	s_waitcnt vmcnt(4)
	s_nop 0
	v_lshlrev_b32_e32 v166, 16, v194
	v_and_b32_e32 v167, 0xffff0000, v194
	v_lshlrev_b32_e32 v168, 16, v195
	v_and_b32_e32 v169, 0xffff0000, v195
	v_lshlrev_b32_e32 v163, 16, v196
	v_and_b32_e32 v170, 0xffff0000, v196
	v_rcp_f32_e32 v162, v166
	v_rcp_f32_e32 v164, v163
	v_rcp_f32_e32 v163, v167
	v_lshlrev_b32_e32 v171, 16, v197
	v_and_b32_e32 v172, 0xffff0000, v197
	v_rcp_f32_e32 v165, v170
	v_lshlrev_b32_e32 v166, 16, v190
	v_and_b32_e32 v167, 0xffff0000, v190
	v_pk_mul_f32 v[162:163], v[162:163], v[166:167]
	v_rcp_f32_e32 v158, v171
	v_pk_mul_f32 v[46:47], v[46:47], v[162:163]
	v_lshlrev_b32_e32 v162, 16, v192
	v_and_b32_e32 v163, 0xffff0000, v192
	v_pk_mul_f32 v[162:163], v[164:165], v[162:163]
	v_lshlrev_b32_e32 v164, 16, v191
	v_pk_mul_f32 v[42:43], v[42:43], v[162:163]
	v_rcp_f32_e32 v162, v168
	v_rcp_f32_e32 v163, v169
	v_and_b32_e32 v165, 0xffff0000, v191
	v_rcp_f32_e32 v159, v172
	v_lshlrev_b32_e32 v160, 16, v193
	v_and_b32_e32 v161, 0xffff0000, v193
	v_pk_mul_f32 v[162:163], v[162:163], v[164:165]
	v_pk_mul_f32 v[158:159], v[158:159], v[160:161]
	v_pk_mul_f32 v[48:49], v[48:49], v[162:163]
	v_pk_mul_f32 v[44:45], v[44:45], v[158:159]
	global_load_dwordx4 v[182:185], v[244:245], off nt
	global_load_dwordx4 v[186:189], v[244:245], off offset:2048 nt
	s_waitcnt vmcnt(4)
	v_lshlrev_b32_e32 v136, 16, v202
	v_and_b32_e32 v137, 0xffff0000, v202
	v_rcp_f32_e32 v136, v136
	v_rcp_f32_e32 v137, v137
	v_lshlrev_b32_e32 v166, 16, v203
	v_and_b32_e32 v167, 0xffff0000, v203
	v_lshlrev_b32_e32 v162, 16, v204
	v_and_b32_e32 v163, 0xffff0000, v204
	v_rcp_f32_e32 v162, v162
	v_rcp_f32_e32 v163, v163
	v_lshlrev_b32_e32 v168, 16, v205
	v_and_b32_e32 v169, 0xffff0000, v205
	v_lshlrev_b32_e32 v164, 16, v198
	v_and_b32_e32 v165, 0xffff0000, v198
	v_pk_mul_f32 v[136:137], v[136:137], v[164:165]
	v_rcp_f32_e32 v158, v168
	v_pk_mul_f32 v[38:39], v[38:39], v[136:137]
	v_lshlrev_b32_e32 v136, 16, v200
	v_and_b32_e32 v137, 0xffff0000, v200
	v_pk_mul_f32 v[136:137], v[162:163], v[136:137]
	v_lshlrev_b32_e32 v162, 16, v199
	v_pk_mul_f32 v[34:35], v[34:35], v[136:137]
	v_rcp_f32_e32 v136, v166
	v_rcp_f32_e32 v137, v167
	v_and_b32_e32 v163, 0xffff0000, v199
	v_rcp_f32_e32 v159, v169
	v_pk_mul_f32 v[136:137], v[136:137], v[162:163]
	s_nop 0
	v_pk_mul_f32 v[40:41], v[40:41], v[136:137]
	v_lshlrev_b32_e32 v136, 16, v201
	v_and_b32_e32 v137, 0xffff0000, v201
	v_pk_mul_f32 v[136:137], v[158:159], v[136:137]
	s_nop 0
	v_pk_mul_f32 v[36:37], v[36:37], v[136:137]
	global_load_dwordx4 v[190:193], v[246:247], off nt
	global_load_dwordx4 v[194:197], v[246:247], off offset:2048 nt
	s_waitcnt vmcnt(4)
	s_nop 0
	v_lshlrev_b32_e32 v166, 16, v178
	v_and_b32_e32 v167, 0xffff0000, v178
	v_lshlrev_b32_e32 v168, 16, v179
	v_and_b32_e32 v169, 0xffff0000, v179
	v_lshlrev_b32_e32 v163, 16, v180
	v_and_b32_e32 v170, 0xffff0000, v180
	v_rcp_f32_e32 v162, v166
	v_rcp_f32_e32 v164, v163
	v_rcp_f32_e32 v163, v167
	v_lshlrev_b32_e32 v171, 16, v181
	v_and_b32_e32 v172, 0xffff0000, v181
	v_rcp_f32_e32 v165, v170
	v_lshlrev_b32_e32 v166, 16, v174
	v_and_b32_e32 v167, 0xffff0000, v174
	v_pk_mul_f32 v[162:163], v[162:163], v[166:167]
	v_rcp_f32_e32 v158, v171
	v_pk_mul_f32 v[30:31], v[30:31], v[162:163]
	v_lshlrev_b32_e32 v162, 16, v176
	v_and_b32_e32 v163, 0xffff0000, v176
	v_pk_mul_f32 v[162:163], v[164:165], v[162:163]
	v_lshlrev_b32_e32 v164, 16, v175
	v_pk_mul_f32 v[26:27], v[26:27], v[162:163]
	v_rcp_f32_e32 v162, v168
	v_rcp_f32_e32 v163, v169
	v_and_b32_e32 v165, 0xffff0000, v175
	v_rcp_f32_e32 v159, v172
	v_lshlrev_b32_e32 v160, 16, v177
	v_and_b32_e32 v161, 0xffff0000, v177
	v_pk_mul_f32 v[162:163], v[162:163], v[164:165]
	v_pk_mul_f32 v[158:159], v[158:159], v[160:161]
	v_pk_mul_f32 v[32:33], v[32:33], v[162:163]
	v_pk_mul_f32 v[28:29], v[28:29], v[158:159]
	global_load_dwordx4 v[198:201], v[248:249], off nt
	global_load_dwordx4 v[202:205], v[248:249], off offset:2048 nt
	s_waitcnt vmcnt(4)
	v_lshlrev_b32_e32 v136, 16, v186
	v_and_b32_e32 v137, 0xffff0000, v186
	v_rcp_f32_e32 v136, v136
	v_rcp_f32_e32 v137, v137
	v_lshlrev_b32_e32 v166, 16, v187
	v_and_b32_e32 v167, 0xffff0000, v187
	v_lshlrev_b32_e32 v162, 16, v188
	v_and_b32_e32 v163, 0xffff0000, v188
	v_rcp_f32_e32 v162, v162
	v_rcp_f32_e32 v163, v163
	v_lshlrev_b32_e32 v168, 16, v189
	v_and_b32_e32 v169, 0xffff0000, v189
	v_lshlrev_b32_e32 v164, 16, v182
	v_and_b32_e32 v165, 0xffff0000, v182
	v_pk_mul_f32 v[136:137], v[136:137], v[164:165]
	v_rcp_f32_e32 v158, v168
	v_pk_mul_f32 v[22:23], v[22:23], v[136:137]
	v_lshlrev_b32_e32 v136, 16, v184
	v_and_b32_e32 v137, 0xffff0000, v184
	v_pk_mul_f32 v[136:137], v[162:163], v[136:137]
	v_lshlrev_b32_e32 v162, 16, v183
	v_pk_mul_f32 v[18:19], v[18:19], v[136:137]
	v_rcp_f32_e32 v136, v166
	v_rcp_f32_e32 v137, v167
	v_and_b32_e32 v163, 0xffff0000, v183
	v_rcp_f32_e32 v159, v169
	v_pk_mul_f32 v[136:137], v[136:137], v[162:163]
	s_nop 0
	v_pk_mul_f32 v[24:25], v[24:25], v[136:137]
	v_lshlrev_b32_e32 v136, 16, v185
	v_and_b32_e32 v137, 0xffff0000, v185
	v_pk_mul_f32 v[136:137], v[158:159], v[136:137]
	s_nop 0
	v_pk_mul_f32 v[20:21], v[20:21], v[136:137]
	s_waitcnt vmcnt(2)
	s_nop 0
	v_and_b32_e32 v163, 0xffff0000, v190
	v_lshlrev_b32_e32 v157, 16, v194
	v_and_b32_e32 v162, 0xffff0000, v194
	v_lshlrev_b32_e32 v164, 16, v195
	v_and_b32_e32 v165, 0xffff0000, v195
	v_lshlrev_b32_e32 v159, 16, v196
	v_and_b32_e32 v166, 0xffff0000, v196
	v_rcp_f32_e32 v158, v157
	v_rcp_f32_e32 v160, v159
	v_rcp_f32_e32 v159, v162
	v_lshlrev_b32_e32 v167, 16, v197
	v_and_b32_e32 v168, 0xffff0000, v197
	v_rcp_f32_e32 v161, v166
	v_lshlrev_b32_e32 v162, 16, v190
	v_pk_mul_f32 v[158:159], v[158:159], v[162:163]
	v_rcp_f32_e32 v134, v167
	v_pk_mul_f32 v[14:15], v[14:15], v[158:159]
	v_lshlrev_b32_e32 v158, 16, v192
	v_and_b32_e32 v159, 0xffff0000, v192
	v_pk_mul_f32 v[158:159], v[160:161], v[158:159]
	v_lshlrev_b32_e32 v160, 16, v191
	v_and_b32_e32 v161, 0xffff0000, v191
	v_rcp_f32_e32 v135, v168
	v_lshlrev_b32_e32 v136, 16, v193
	v_and_b32_e32 v137, 0xffff0000, v193
	v_pk_mul_f32 v[10:11], v[10:11], v[158:159]
	v_pk_mul_f32 v[134:135], v[134:135], v[136:137]
	v_rcp_f32_e32 v158, v164
	v_pk_mul_f32 v[12:13], v[12:13], v[134:135]
	s_waitcnt vmcnt(0)
	s_nop 0
	v_rcp_f32_e32 v159, v165
	v_lshlrev_b32_e32 v157, 16, v202
	v_pk_mul_f32 v[158:159], v[158:159], v[160:161]
	v_lshlrev_b32_e32 v160, 16, v203
	v_pk_mul_f32 v[16:17], v[16:17], v[158:159]
	v_and_b32_e32 v158, 0xffff0000, v202
	v_and_b32_e32 v161, 0xffff0000, v203
	v_lshlrev_b32_e32 v135, 16, v204
	v_and_b32_e32 v162, 0xffff0000, v204
	v_rcp_f32_e32 v134, v157
	v_rcp_f32_e32 v136, v135
	v_rcp_f32_e32 v135, v158
	v_lshlrev_b32_e32 v163, 16, v205
	v_and_b32_e32 v164, 0xffff0000, v205
	v_rcp_f32_e32 v137, v162
	v_lshlrev_b32_e32 v158, 16, v198
	v_and_b32_e32 v159, 0xffff0000, v198
	v_pk_mul_f32 v[134:135], v[134:135], v[158:159]
	v_rcp_f32_e32 v130, v163
	v_pk_mul_f32 v[6:7], v[6:7], v[134:135]
	v_lshlrev_b32_e32 v134, 16, v200
	v_and_b32_e32 v135, 0xffff0000, v200
	v_pk_mul_f32 v[134:135], v[136:137], v[134:135]
	v_lshlrev_b32_e32 v136, 16, v199
	v_pk_mul_f32 v[2:3], v[2:3], v[134:135]
	v_rcp_f32_e32 v134, v160
	v_rcp_f32_e32 v135, v161
	v_and_b32_e32 v137, 0xffff0000, v199
	v_rcp_f32_e32 v131, v164
	v_lshlrev_b32_e32 v132, 16, v201
	v_and_b32_e32 v133, 0xffff0000, v201
	v_pk_mul_f32 v[134:135], v[134:135], v[136:137]
	v_pk_mul_f32 v[130:131], v[130:131], v[132:133]
	v_pk_mul_f32 v[8:9], v[8:9], v[134:135]
	v_pk_mul_f32 v[4:5], v[4:5], v[130:131]
	s_branch .LBB0_255

.LBB0_266:
	v_mov_b32_e32 v130, v1
	v_mov_b32_e32 v131, v154
	s_add_i32 s93, s93, s64
	s_or_b32 s0, s92, s65
	v_mov_b64_e32 v[134:135], s[10:11]
	v_add_u32_e32 v132, s93, v130
	v_lshl_add_u32 v136, v131, 3, s0
	v_mad_i64_i32 v[130:131], s[0:1], v132, s24, v[134:135]
	s_mov_b64 s[18:19], 0x1000
	v_ashrrev_i32_e32 v137, 31, v136
	v_lshl_add_u64 v[160:161], v[130:131], 0, s[18:19]
	v_lshlrev_b64 v[130:131], 1, v[136:137]
	v_lshl_add_u64 v[150:151], v[160:161], 0, v[130:131]
	global_load_dwordx4 v[150:153], v[150:151], off nt
	v_ashrrev_i32_e32 v133, 31, v132
	v_lshlrev_b64 v[158:159], 11, v[132:133]
	s_and_b64 vcc, exec, s[4:5]
	s_mov_b32 s97, 0x10000
	s_mov_b32 s96, 0x12000
	s_mov_b32 s89, 0x16000
	s_movk_i32 s95, 0x3c0
	s_mov_b32 s92, 0xfe5163ab
	s_mov_b32 s93, 0x3c439041
	s_mov_b32 s94, 0xdb629599
	s_waitcnt vmcnt(0)
	v_lshlrev_b32_e32 v162, 16, v150
	v_and_b32_e32 v163, 0xffff0000, v150
	v_lshlrev_b32_e32 v150, 16, v151
	v_and_b32_e32 v151, 0xffff0000, v151
	v_lshlrev_b32_e32 v164, 16, v152
	v_and_b32_e32 v165, 0xffff0000, v152
	v_lshlrev_b32_e32 v152, 16, v153
	v_and_b32_e32 v153, 0xffff0000, v153
	v_pk_mul_f32 v[126:127], v[126:127], v[162:163]
	v_pk_mul_f32 v[128:129], v[128:129], v[150:151]
	v_pk_mul_f32 v[150:151], v[124:125], v[152:153]
	v_pk_mul_f32 v[124:125], v[122:123], v[164:165]
	v_cvt_pk_bf16_f32 v122, v126, v127
	v_lshl_add_u64 v[126:127], s[12:13], 0, v[158:159]
	v_cvt_pk_bf16_f32 v123, v128, v129
	v_cvt_pk_bf16_f32 v124, v124, v125
	v_cvt_pk_bf16_f32 v125, v150, v151
	v_lshl_add_u64 v[128:129], v[126:127], 0, v[130:131]
	global_store_dwordx4 v[128:129], v[122:125], off
	s_nop 1
	v_add_u32_e32 v122, 0x80, v136
	v_ashrrev_i32_e32 v123, 31, v122
	v_lshlrev_b64 v[122:123], 1, v[122:123]
	v_lshl_add_u64 v[124:125], v[160:161], 0, v[122:123]
	global_load_dwordx4 v[124:127], v[124:125], off nt
	s_waitcnt vmcnt(0)
	v_lshlrev_b32_e32 v136, 16, v124
	v_and_b32_e32 v137, 0xffff0000, v124
	v_lshlrev_b32_e32 v124, 16, v125
	v_and_b32_e32 v125, 0xffff0000, v125
	v_lshlrev_b32_e32 v150, 16, v126
	v_and_b32_e32 v151, 0xffff0000, v126
	v_lshlrev_b32_e32 v126, 16, v127
	v_and_b32_e32 v127, 0xffff0000, v127
	v_pk_mul_f32 v[120:121], v[120:121], v[124:125]
	v_pk_mul_f32 v[118:119], v[118:119], v[136:137]
	v_pk_mul_f32 v[124:125], v[116:117], v[126:127]
	v_pk_mul_f32 v[116:117], v[114:115], v[150:151]
	v_cvt_pk_bf16_f32 v114, v118, v119
	v_cvt_pk_bf16_f32 v115, v120, v121
	v_cvt_pk_bf16_f32 v116, v116, v117
	v_cvt_pk_bf16_f32 v117, v124, v125
	global_store_dwordx4 v[128:129], v[114:117], off offset:256
	s_nop 1
	v_add_u32_e32 v114, 16, v132
	v_ashrrev_i32_e32 v115, 31, v114
	v_lshlrev_b64 v[118:119], 11, v[114:115]
	v_mad_i64_i32 v[114:115], s[0:1], v114, s24, v[134:135]
	v_lshl_add_u64 v[120:121], v[114:115], 0, s[18:19]
	v_lshl_add_u64 v[114:115], v[120:121], 0, v[130:131]
	global_load_dwordx4 v[114:117], v[114:115], off nt
	s_waitcnt vmcnt(0)
	v_lshlrev_b32_e32 v124, 16, v114
	v_and_b32_e32 v125, 0xffff0000, v114
	v_lshlrev_b32_e32 v114, 16, v115
	v_and_b32_e32 v115, 0xffff0000, v115
	v_lshlrev_b32_e32 v126, 16, v116
	v_and_b32_e32 v127, 0xffff0000, v116
	v_lshlrev_b32_e32 v116, 16, v117
	v_and_b32_e32 v117, 0xffff0000, v117
	v_pk_mul_f32 v[110:111], v[110:111], v[124:125]
	v_pk_mul_f32 v[112:113], v[112:113], v[114:115]
	v_pk_mul_f32 v[114:115], v[108:109], v[116:117]
	v_pk_mul_f32 v[108:109], v[106:107], v[126:127]
	v_cvt_pk_bf16_f32 v106, v110, v111
	v_lshl_add_u64 v[110:111], s[12:13], 0, v[118:119]
	v_cvt_pk_bf16_f32 v107, v112, v113
	v_cvt_pk_bf16_f32 v108, v108, v109
	v_cvt_pk_bf16_f32 v109, v114, v115
	v_lshl_add_u64 v[110:111], v[110:111], 0, v[130:131]
	global_store_dwordx4 v[110:111], v[106:109], off
	s_nop 1
	v_lshl_add_u64 v[106:107], v[120:121], 0, v[122:123]
	global_load_dwordx4 v[106:109], v[106:107], off nt
	s_waitcnt vmcnt(0)
	v_lshlrev_b32_e32 v112, 16, v106
	v_and_b32_e32 v113, 0xffff0000, v106
	v_lshlrev_b32_e32 v106, 16, v107
	v_and_b32_e32 v107, 0xffff0000, v107
	v_lshlrev_b32_e32 v114, 16, v108
	v_and_b32_e32 v115, 0xffff0000, v108
	v_lshlrev_b32_e32 v108, 16, v109
	v_and_b32_e32 v109, 0xffff0000, v109
	v_pk_mul_f32 v[104:105], v[104:105], v[106:107]
	v_pk_mul_f32 v[102:103], v[102:103], v[112:113]
	v_pk_mul_f32 v[106:107], v[100:101], v[108:109]
	v_pk_mul_f32 v[100:101], v[98:99], v[114:115]
	v_cvt_pk_bf16_f32 v98, v102, v103
	v_cvt_pk_bf16_f32 v99, v104, v105
	v_cvt_pk_bf16_f32 v100, v100, v101
	v_cvt_pk_bf16_f32 v101, v106, v107
	global_store_dwordx4 v[110:111], v[98:101], off offset:256
	s_nop 1
	v_add_u32_e32 v98, 32, v132
	v_ashrrev_i32_e32 v99, 31, v98
	v_lshlrev_b64 v[102:103], 11, v[98:99]
	v_mad_i64_i32 v[98:99], s[0:1], v98, s24, v[134:135]
	v_lshl_add_u64 v[104:105], v[98:99], 0, s[18:19]
	v_lshl_add_u64 v[98:99], v[104:105], 0, v[130:131]
	global_load_dwordx4 v[98:101], v[98:99], off nt
	s_waitcnt vmcnt(0)
	v_lshlrev_b32_e32 v106, 16, v98
	v_and_b32_e32 v107, 0xffff0000, v98
	v_lshlrev_b32_e32 v98, 16, v99
	v_and_b32_e32 v99, 0xffff0000, v99
	v_lshlrev_b32_e32 v108, 16, v100
	v_and_b32_e32 v109, 0xffff0000, v100
	v_lshlrev_b32_e32 v100, 16, v101
	v_and_b32_e32 v101, 0xffff0000, v101
	v_pk_mul_f32 v[94:95], v[94:95], v[106:107]
	v_pk_mul_f32 v[96:97], v[96:97], v[98:99]
	v_pk_mul_f32 v[98:99], v[92:93], v[100:101]
	v_pk_mul_f32 v[92:93], v[90:91], v[108:109]
	v_cvt_pk_bf16_f32 v90, v94, v95
	v_lshl_add_u64 v[94:95], s[12:13], 0, v[102:103]
	v_cvt_pk_bf16_f32 v91, v96, v97
	v_cvt_pk_bf16_f32 v92, v92, v93
	v_cvt_pk_bf16_f32 v93, v98, v99
	v_lshl_add_u64 v[94:95], v[94:95], 0, v[130:131]
	global_store_dwordx4 v[94:95], v[90:93], off
	s_nop 1
	v_lshl_add_u64 v[90:91], v[104:105], 0, v[122:123]
	global_load_dwordx4 v[90:93], v[90:91], off nt
	s_waitcnt vmcnt(0)
	v_lshlrev_b32_e32 v96, 16, v90
	v_and_b32_e32 v97, 0xffff0000, v90
	v_lshlrev_b32_e32 v90, 16, v91
	v_and_b32_e32 v91, 0xffff0000, v91
	v_lshlrev_b32_e32 v98, 16, v92
	v_and_b32_e32 v99, 0xffff0000, v92
	v_lshlrev_b32_e32 v92, 16, v93
	v_and_b32_e32 v93, 0xffff0000, v93
	v_pk_mul_f32 v[88:89], v[88:89], v[90:91]
	v_pk_mul_f32 v[86:87], v[86:87], v[96:97]
	v_pk_mul_f32 v[90:91], v[84:85], v[92:93]
	v_pk_mul_f32 v[84:85], v[82:83], v[98:99]
	v_cvt_pk_bf16_f32 v82, v86, v87
	v_cvt_pk_bf16_f32 v83, v88, v89
	v_cvt_pk_bf16_f32 v84, v84, v85
	v_cvt_pk_bf16_f32 v85, v90, v91
	global_store_dwordx4 v[94:95], v[82:85], off offset:256
	s_nop 1
	v_add_u32_e32 v82, 48, v132
	v_ashrrev_i32_e32 v83, 31, v82
	v_lshlrev_b64 v[86:87], 11, v[82:83]
	v_mad_i64_i32 v[82:83], s[0:1], v82, s24, v[134:135]
	v_lshl_add_u64 v[88:89], v[82:83], 0, s[18:19]
	v_lshl_add_u64 v[82:83], v[88:89], 0, v[130:131]
	global_load_dwordx4 v[82:85], v[82:83], off nt
	s_waitcnt vmcnt(0)
	v_lshlrev_b32_e32 v90, 16, v82
	v_and_b32_e32 v91, 0xffff0000, v82
	v_lshlrev_b32_e32 v82, 16, v83
	v_and_b32_e32 v83, 0xffff0000, v83
	v_lshlrev_b32_e32 v92, 16, v84
	v_and_b32_e32 v93, 0xffff0000, v84
	v_lshlrev_b32_e32 v84, 16, v85
	v_and_b32_e32 v85, 0xffff0000, v85
	v_pk_mul_f32 v[78:79], v[78:79], v[90:91]
	v_pk_mul_f32 v[80:81], v[80:81], v[82:83]
	v_pk_mul_f32 v[82:83], v[76:77], v[84:85]
	v_pk_mul_f32 v[76:77], v[74:75], v[92:93]
	v_cvt_pk_bf16_f32 v74, v78, v79
	v_lshl_add_u64 v[78:79], s[12:13], 0, v[86:87]
	v_cvt_pk_bf16_f32 v75, v80, v81
	v_cvt_pk_bf16_f32 v76, v76, v77
	v_cvt_pk_bf16_f32 v77, v82, v83
	v_lshl_add_u64 v[78:79], v[78:79], 0, v[130:131]
	global_store_dwordx4 v[78:79], v[74:77], off
	s_nop 1
	v_lshl_add_u64 v[74:75], v[88:89], 0, v[122:123]
	global_load_dwordx4 v[74:77], v[74:75], off nt
	s_waitcnt vmcnt(0)
	v_lshlrev_b32_e32 v80, 16, v74
	v_and_b32_e32 v81, 0xffff0000, v74
	v_lshlrev_b32_e32 v74, 16, v75
	v_and_b32_e32 v75, 0xffff0000, v75
	v_lshlrev_b32_e32 v82, 16, v76
	v_and_b32_e32 v83, 0xffff0000, v76
	v_lshlrev_b32_e32 v76, 16, v77
	v_and_b32_e32 v77, 0xffff0000, v77
	v_pk_mul_f32 v[72:73], v[72:73], v[74:75]
	v_pk_mul_f32 v[70:71], v[70:71], v[80:81]
	v_pk_mul_f32 v[74:75], v[68:69], v[76:77]
	v_pk_mul_f32 v[68:69], v[66:67], v[82:83]
	v_cvt_pk_bf16_f32 v66, v70, v71
	v_cvt_pk_bf16_f32 v67, v72, v73
	v_cvt_pk_bf16_f32 v68, v68, v69
	v_cvt_pk_bf16_f32 v69, v74, v75
	global_store_dwordx4 v[78:79], v[66:69], off offset:256
	s_nop 1
	v_add_u32_e32 v66, 0x80, v132
	v_ashrrev_i32_e32 v67, 31, v66
	v_lshlrev_b64 v[70:71], 11, v[66:67]
	v_mad_i64_i32 v[66:67], s[0:1], v66, s24, v[134:135]
	v_lshl_add_u64 v[72:73], v[66:67], 0, s[18:19]
	v_lshl_add_u64 v[66:67], v[72:73], 0, v[130:131]
	global_load_dwordx4 v[66:69], v[66:67], off nt
	s_waitcnt vmcnt(0)
	v_lshlrev_b32_e32 v74, 16, v66
	v_and_b32_e32 v75, 0xffff0000, v66
	v_lshlrev_b32_e32 v66, 16, v67
	v_and_b32_e32 v67, 0xffff0000, v67
	v_lshlrev_b32_e32 v76, 16, v68
	v_and_b32_e32 v77, 0xffff0000, v68
	v_lshlrev_b32_e32 v68, 16, v69
	v_and_b32_e32 v69, 0xffff0000, v69
	v_pk_mul_f32 v[62:63], v[62:63], v[74:75]
	v_pk_mul_f32 v[64:65], v[64:65], v[66:67]
	v_pk_mul_f32 v[66:67], v[60:61], v[68:69]
	v_pk_mul_f32 v[60:61], v[58:59], v[76:77]
	v_cvt_pk_bf16_f32 v58, v62, v63
	v_lshl_add_u64 v[62:63], s[12:13], 0, v[70:71]
	v_cvt_pk_bf16_f32 v59, v64, v65
	v_cvt_pk_bf16_f32 v60, v60, v61
	v_cvt_pk_bf16_f32 v61, v66, v67
	v_lshl_add_u64 v[62:63], v[62:63], 0, v[130:131]
	global_store_dwordx4 v[62:63], v[58:61], off
	s_nop 1
	v_lshl_add_u64 v[58:59], v[72:73], 0, v[122:123]
	global_load_dwordx4 v[58:61], v[58:59], off nt
	s_waitcnt vmcnt(0)
	v_lshlrev_b32_e32 v64, 16, v58
	v_and_b32_e32 v65, 0xffff0000, v58
	v_lshlrev_b32_e32 v58, 16, v59
	v_and_b32_e32 v59, 0xffff0000, v59
	v_lshlrev_b32_e32 v66, 16, v60
	v_and_b32_e32 v67, 0xffff0000, v60
	v_lshlrev_b32_e32 v60, 16, v61
	v_and_b32_e32 v61, 0xffff0000, v61
	v_pk_mul_f32 v[56:57], v[56:57], v[58:59]
	v_pk_mul_f32 v[54:55], v[54:55], v[64:65]
	v_pk_mul_f32 v[58:59], v[52:53], v[60:61]
	v_pk_mul_f32 v[52:53], v[50:51], v[66:67]
	v_cvt_pk_bf16_f32 v50, v54, v55
	v_cvt_pk_bf16_f32 v51, v56, v57
	v_cvt_pk_bf16_f32 v52, v52, v53
	v_cvt_pk_bf16_f32 v53, v58, v59
	global_store_dwordx4 v[62:63], v[50:53], off offset:256
	s_nop 1
	v_add_u32_e32 v50, 0x90, v132
	v_ashrrev_i32_e32 v51, 31, v50
	v_lshlrev_b64 v[54:55], 11, v[50:51]
	v_mad_i64_i32 v[50:51], s[0:1], v50, s24, v[134:135]
	v_lshl_add_u64 v[56:57], v[50:51], 0, s[18:19]
	v_lshl_add_u64 v[50:51], v[56:57], 0, v[130:131]
	global_load_dwordx4 v[50:53], v[50:51], off nt
	s_waitcnt vmcnt(0)
	v_lshlrev_b32_e32 v58, 16, v50
	v_and_b32_e32 v59, 0xffff0000, v50
	v_lshlrev_b32_e32 v50, 16, v51
	v_and_b32_e32 v51, 0xffff0000, v51
	v_lshlrev_b32_e32 v60, 16, v52
	v_and_b32_e32 v61, 0xffff0000, v52
	v_lshlrev_b32_e32 v52, 16, v53
	v_and_b32_e32 v53, 0xffff0000, v53
	v_pk_mul_f32 v[46:47], v[46:47], v[58:59]
	v_pk_mul_f32 v[48:49], v[48:49], v[50:51]
	v_pk_mul_f32 v[50:51], v[44:45], v[52:53]
	v_pk_mul_f32 v[44:45], v[42:43], v[60:61]
	v_cvt_pk_bf16_f32 v42, v46, v47
	v_lshl_add_u64 v[46:47], s[12:13], 0, v[54:55]
	v_cvt_pk_bf16_f32 v43, v48, v49
	v_cvt_pk_bf16_f32 v44, v44, v45
	v_cvt_pk_bf16_f32 v45, v50, v51
	v_lshl_add_u64 v[46:47], v[46:47], 0, v[130:131]
	global_store_dwordx4 v[46:47], v[42:45], off
	s_nop 1
	v_lshl_add_u64 v[42:43], v[56:57], 0, v[122:123]
	global_load_dwordx4 v[42:45], v[42:43], off nt
	s_waitcnt vmcnt(0)
	v_lshlrev_b32_e32 v48, 16, v42
	v_and_b32_e32 v49, 0xffff0000, v42
	v_lshlrev_b32_e32 v42, 16, v43
	v_and_b32_e32 v43, 0xffff0000, v43
	v_lshlrev_b32_e32 v50, 16, v44
	v_and_b32_e32 v51, 0xffff0000, v44
	v_lshlrev_b32_e32 v44, 16, v45
	v_and_b32_e32 v45, 0xffff0000, v45
	v_pk_mul_f32 v[40:41], v[40:41], v[42:43]
	v_pk_mul_f32 v[38:39], v[38:39], v[48:49]
	v_pk_mul_f32 v[42:43], v[36:37], v[44:45]
	v_pk_mul_f32 v[36:37], v[34:35], v[50:51]
	v_cvt_pk_bf16_f32 v34, v38, v39
	v_cvt_pk_bf16_f32 v35, v40, v41
	v_cvt_pk_bf16_f32 v36, v36, v37
	v_cvt_pk_bf16_f32 v37, v42, v43
	global_store_dwordx4 v[46:47], v[34:37], off offset:256
	s_nop 1
	v_add_u32_e32 v34, 0xa0, v132
	v_ashrrev_i32_e32 v35, 31, v34
	v_lshlrev_b64 v[38:39], 11, v[34:35]
	v_mad_i64_i32 v[34:35], s[0:1], v34, s24, v[134:135]
	v_lshl_add_u64 v[40:41], v[34:35], 0, s[18:19]
	v_lshl_add_u64 v[34:35], v[40:41], 0, v[130:131]
	global_load_dwordx4 v[34:37], v[34:35], off nt
	s_waitcnt vmcnt(0)
	v_lshlrev_b32_e32 v42, 16, v34
	v_and_b32_e32 v43, 0xffff0000, v34
	v_lshlrev_b32_e32 v34, 16, v35
	v_and_b32_e32 v35, 0xffff0000, v35
	v_lshlrev_b32_e32 v44, 16, v36
	v_and_b32_e32 v45, 0xffff0000, v36
	v_lshlrev_b32_e32 v36, 16, v37
	v_and_b32_e32 v37, 0xffff0000, v37
	v_pk_mul_f32 v[30:31], v[30:31], v[42:43]
	v_pk_mul_f32 v[32:33], v[32:33], v[34:35]
	v_pk_mul_f32 v[34:35], v[28:29], v[36:37]
	v_pk_mul_f32 v[28:29], v[26:27], v[44:45]
	v_cvt_pk_bf16_f32 v26, v30, v31
	v_lshl_add_u64 v[30:31], s[12:13], 0, v[38:39]
	v_cvt_pk_bf16_f32 v27, v32, v33
	v_cvt_pk_bf16_f32 v28, v28, v29
	v_cvt_pk_bf16_f32 v29, v34, v35
	v_lshl_add_u64 v[30:31], v[30:31], 0, v[130:131]
	global_store_dwordx4 v[30:31], v[26:29], off
	s_nop 1
	v_lshl_add_u64 v[26:27], v[40:41], 0, v[122:123]
	global_load_dwordx4 v[26:29], v[26:27], off nt
	s_waitcnt vmcnt(0)
	v_lshlrev_b32_e32 v32, 16, v26
	v_and_b32_e32 v33, 0xffff0000, v26
	v_lshlrev_b32_e32 v26, 16, v27
	v_and_b32_e32 v27, 0xffff0000, v27
	v_lshlrev_b32_e32 v34, 16, v28
	v_and_b32_e32 v35, 0xffff0000, v28
	v_lshlrev_b32_e32 v28, 16, v29
	v_and_b32_e32 v29, 0xffff0000, v29
	v_pk_mul_f32 v[24:25], v[24:25], v[26:27]
	v_pk_mul_f32 v[22:23], v[22:23], v[32:33]
	v_pk_mul_f32 v[26:27], v[20:21], v[28:29]
	v_pk_mul_f32 v[20:21], v[18:19], v[34:35]
	v_cvt_pk_bf16_f32 v18, v22, v23
	v_cvt_pk_bf16_f32 v19, v24, v25
	v_cvt_pk_bf16_f32 v20, v20, v21
	v_cvt_pk_bf16_f32 v21, v26, v27
	global_store_dwordx4 v[30:31], v[18:21], off offset:256
	s_nop 1
	v_add_u32_e32 v18, 0xb0, v132
	v_ashrrev_i32_e32 v19, 31, v18
	v_lshlrev_b64 v[22:23], 11, v[18:19]
	v_mad_i64_i32 v[18:19], s[0:1], v18, s24, v[134:135]
	v_lshl_add_u64 v[24:25], v[18:19], 0, s[18:19]
	v_lshl_add_u64 v[18:19], v[24:25], 0, v[130:131]
	global_load_dwordx4 v[18:21], v[18:19], off nt
	s_mov_b64 s[18:19], -1
	s_waitcnt vmcnt(0)
	v_lshlrev_b32_e32 v26, 16, v18
	v_and_b32_e32 v27, 0xffff0000, v18
	v_lshlrev_b32_e32 v18, 16, v19
	v_and_b32_e32 v19, 0xffff0000, v19
	v_lshlrev_b32_e32 v28, 16, v20
	v_and_b32_e32 v29, 0xffff0000, v20
	v_lshlrev_b32_e32 v20, 16, v21
	v_and_b32_e32 v21, 0xffff0000, v21
	v_pk_mul_f32 v[14:15], v[14:15], v[26:27]
	v_pk_mul_f32 v[16:17], v[16:17], v[18:19]
	v_pk_mul_f32 v[18:19], v[12:13], v[20:21]
	v_pk_mul_f32 v[12:13], v[10:11], v[28:29]
	v_cvt_pk_bf16_f32 v10, v14, v15
	v_lshl_add_u64 v[14:15], s[12:13], 0, v[22:23]
	v_cvt_pk_bf16_f32 v11, v16, v17
	v_cvt_pk_bf16_f32 v12, v12, v13
	v_cvt_pk_bf16_f32 v13, v18, v19
	v_lshl_add_u64 v[14:15], v[14:15], 0, v[130:131]
	global_store_dwordx4 v[14:15], v[10:13], off
	s_nop 1
	v_lshl_add_u64 v[10:11], v[24:25], 0, v[122:123]
	global_load_dwordx4 v[10:13], v[10:11], off nt
	s_waitcnt vmcnt(0)
	v_lshlrev_b32_e32 v16, 16, v10
	v_and_b32_e32 v17, 0xffff0000, v10
	v_lshlrev_b32_e32 v10, 16, v11
	v_and_b32_e32 v11, 0xffff0000, v11
	v_lshlrev_b32_e32 v18, 16, v12
	v_and_b32_e32 v19, 0xffff0000, v12
	v_lshlrev_b32_e32 v12, 16, v13
	v_and_b32_e32 v13, 0xffff0000, v13
	v_pk_mul_f32 v[8:9], v[8:9], v[10:11]
	v_pk_mul_f32 v[6:7], v[6:7], v[16:17]
	v_pk_mul_f32 v[10:11], v[4:5], v[12:13]
	v_pk_mul_f32 v[4:5], v[2:3], v[18:19]
	v_cvt_pk_bf16_f32 v2, v6, v7
	v_cvt_pk_bf16_f32 v3, v8, v9
	v_cvt_pk_bf16_f32 v4, v4, v5
	v_cvt_pk_bf16_f32 v5, v10, v11
	global_store_dwordx4 v[14:15], v[2:5], off offset:256
	s_cbranch_vccnz .LBB0_243
	s_andn2_b64 vcc, exec, s[8:9]
	s_cbranch_vccnz .LBB0_242
	s_barrier
	s_branch .LBB0_242
